# VWK
# speedup vs baseline: 1.0046x; 1.0044x over previous
; template <int MODE> ...
;     ...
;         const float negm = sel ? -m_new : -1e30f;
;         float ps4[4];
; #pragma unroll
;         for (int mt = 0; mt < 4; ++mt) {
; #pragma unroll
;           for (int jj = 0; jj < 4; ++jj) s[qs][mt][jj] = __builtin_amdgcn_exp2f(fmaf(s[qs][mt][jj], SCL, negm));
;           ps4[mt] = (s[qs][mt][0] + s[qs][mt][1]) + (s[qs][mt][2] + s[qs][mt][3]);
;         }
;         l_run[qs] = l_run[qs] * alpha[qs] + ((ps4[0] + ps4[1]) + (ps4[2] + ps4[3]));
; #pragma unroll
;         for (int kk = 0; kk < 2; ++kk) {
;           uint4 pk;
;           pk.x = pack2(s[qs][2 * kk][0], s[qs][2 * kk][1]);
;           pk.y = pack2(s[qs][2 * kk][2], s[qs][2 * kk][3]);
;           pk.z = pack2(s[qs][2 * kk + 1][0], s[qs][2 * kk + 1][1]);
;           pk.w = pack2(s[qs][2 * kk + 1][2], s[qs][2 * kk + 1][3]);
;           pb[qs][kk] = *reinterpret_cast<bf16x8*>(&pk);
;         }
;       }
;       if (__ballot(alpha[0] != 1.0f || alpha[1] != 1.0f) != 0ull) {
; #pragma unroll
;         for (int qs = 0; qs < 2; ++qs)
; #pragma unroll
;           for (int dt = 0; dt < 8; ++dt) {
;             o[qs][dt][0] *= alpha[qs]; o[qs][dt][1] *= alpha[qs]; o[qs][dt][2] *= alpha[qs]; o[qs][dt][3] *= alpha[qs];
;           }
;       }
; #pragma unroll
;       for (int kk = 0; kk < 2; ++kk)
; #pragma unroll
;         for (int dt = 0; dt < 8; ++dt) {
;           bf16x8 a = *(const bf16x8*)(Vt + (dt * 16 + c) * VT_STRIDE + kk * 32 + quad * 8);
;           o[0][dt] = __builtin_amdgcn_mfma_f32_16x16x32_bf16(a, pb[0][kk], o[0][dt], 0, 0, 0);
;           o[1][dt] = __builtin_amdgcn_mfma_f32_16x16x32_bf16(a, pb[1][kk], o[1][dt], 0, 0, 0);
;         }
.LBB0_321:
	v_cndmask_b32_e64 v169, -v148, v214, s[10:11]
	v_fmamk_f32 v125, v125, 0x3e0293ee, v169
	v_exp_f32_e32 v168, v125
	v_fmamk_f32 v125, v126, 0x3e0293ee, v169
	v_cndmask_b32_e64 v126, -v149, v214, s[8:9]
	v_fmamk_f32 v128, v128, 0x3e0293ee, v169
	v_fmamk_f32 v136, v136, 0x3e0293ee, v126
	v_exp_f32_e32 v152, v128
	v_fmamk_f32 v128, v129, 0x3e0293ee, v169
	v_exp_f32_e32 v153, v136
	v_fmamk_f32 v136, v137, 0x3e0293ee, v126
	v_exp_f32_e32 v156, v128
	v_fmamk_f32 v128, v130, 0x3e0293ee, v169
	v_exp_f32_e32 v157, v136
	v_fmamk_f32 v136, v138, 0x3e0293ee, v126
	v_exp_f32_e32 v154, v128
	v_fmamk_f32 v128, v131, 0x3e0293ee, v169
	v_exp_f32_e32 v155, v136
	v_fmamk_f32 v136, v139, 0x3e0293ee, v126
	v_add_u32_e32 v183, v167, v177
	v_exp_f32_e32 v158, v128
	v_fmamk_f32 v128, v140, 0x3e0293ee, v169
	v_exp_f32_e32 v159, v136
	v_fmamk_f32 v132, v132, 0x3e0293ee, v126
	ds_read_b128 v[136:139], v183 offset:17408
	v_exp_f32_e32 v140, v128
	v_fmamk_f32 v128, v141, 0x3e0293ee, v169
	v_exp_f32_e32 v141, v132
	v_fmamk_f32 v132, v133, 0x3e0293ee, v126
	v_exp_f32_e32 v164, v128
	v_fmamk_f32 v128, v142, 0x3e0293ee, v169
	v_exp_f32_e32 v165, v132
	v_fmamk_f32 v132, v134, 0x3e0293ee, v126
	v_exp_f32_e32 v142, v128
	v_fmamk_f32 v128, v143, 0x3e0293ee, v169
	v_exp_f32_e32 v143, v132
	v_fmamk_f32 v132, v135, 0x3e0293ee, v126
	v_exp_f32_e32 v166, v128
	v_exp_f32_e32 v167, v132
	ds_read_b128 v[196:199], v183 offset:19712
	ds_read_b128 v[200:203], v183 offset:17472
	v_cvt_pk_bf16_f32 v128, v152, v156
	v_cvt_pk_bf16_f32 v129, v154, v158
	v_cvt_pk_bf16_f32 v130, v140, v164
	v_cvt_pk_bf16_f32 v131, v142, v166
	v_cvt_pk_bf16_f32 v132, v153, v157
	v_cvt_pk_bf16_f32 v133, v155, v159
	v_cvt_pk_bf16_f32 v134, v141, v165
	v_cvt_pk_bf16_f32 v135, v143, v167
	s_waitcnt lgkmcnt(2)
	v_mfma_f32_16x16x32_bf16 v[92:95], v[136:139], v[128:131], v[92:95]
	v_fmamk_f32 v120, v120, 0x3e0293ee, v169
	v_exp_f32_e32 v208, v125
	v_fmamk_f32 v125, v127, 0x3e0293ee, v169
	v_mfma_f32_16x16x32_bf16 v[88:91], v[136:139], v[132:135], v[88:91]
	ds_read_b128 v[136:139], v183 offset:22016
	ds_read_b128 v[204:207], v183 offset:19776
	v_exp_f32_e32 v240, v120
	v_fmamk_f32 v120, v121, 0x3e0293ee, v169
	s_waitcnt lgkmcnt(3)
	v_mfma_f32_16x16x32_bf16 v[84:87], v[196:199], v[128:131], v[84:87]
	v_fmamk_f32 v116, v116, 0x3e0293ee, v126
	v_fmamk_f32 v124, v124, 0x3e0293ee, v169
	v_exp_f32_e32 v238, v125
	v_mfma_f32_16x16x32_bf16 v[80:83], v[196:199], v[132:135], v[80:83]
	ds_read_b128 v[196:199], v183 offset:24320
	ds_read_b128 v[218:221], v183 offset:22080
	v_exp_f32_e32 v242, v120
	v_fmamk_f32 v120, v122, 0x3e0293ee, v169
	s_waitcnt lgkmcnt(3)
	v_mfma_f32_16x16x32_bf16 v[76:79], v[136:139], v[128:131], v[76:79]
	v_fmac_f32_e32 v169, 0x3e0293ee, v123
	v_exp_f32_e32 v125, v116
	v_fmamk_f32 v116, v117, 0x3e0293ee, v126
	v_mfma_f32_16x16x32_bf16 v[72:75], v[136:139], v[132:135], v[72:75]
	ds_read_b128 v[136:139], v183 offset:26624
	ds_read_b128 v[222:225], v183 offset:24384
	v_exp_f32_e32 v246, v169
	v_exp_f32_e32 v169, v116
	s_waitcnt lgkmcnt(3)
	v_mfma_f32_16x16x32_bf16 v[68:71], v[196:199], v[128:131], v[68:71]
	v_fmamk_f32 v116, v118, 0x3e0293ee, v126
	v_exp_f32_e32 v209, v116
	v_fmamk_f32 v116, v119, 0x3e0293ee, v126
	v_mfma_f32_16x16x32_bf16 v[64:67], v[196:199], v[132:135], v[64:67]
	ds_read_b128 v[196:199], v183 offset:28928
	ds_read_b128 v[226:229], v183 offset:26688
	v_exp_f32_e32 v239, v116
	v_fmamk_f32 v112, v112, 0x3e0293ee, v126
	s_waitcnt lgkmcnt(3)
; template <int MODE> ...
;     ...
;           for (int jj = 0; jj < 4; ++jj) s[qs][mt][jj] = __builtin_amdgcn_exp2f(fmaf(s[qs][mt][jj], SCL, negm));
;           ps4[mt] = (s[qs][mt][0] + s[qs][mt][1]) + (s[qs][mt][2] + s[qs][mt][3]);
;         }
;         l_run[qs] = l_run[qs] * alpha[qs] + ((ps4[0] + ps4[1]) + (ps4[2] + ps4[3]));
; #pragma unroll
;         for (int kk = 0; kk < 2; ++kk) {
;           uint4 pk;
;           pk.x = pack2(s[qs][2 * kk][0], s[qs][2 * kk][1]);
;           pk.y = pack2(s[qs][2 * kk][2], s[qs][2 * kk][3]);
;           pk.z = pack2(s[qs][2 * kk + 1][0], s[qs][2 * kk + 1][1]);
;           pk.w = pack2(s[qs][2 * kk + 1][2], s[qs][2 * kk + 1][3]);
;           pb[qs][kk] = *reinterpret_cast<bf16x8*>(&pk);
;         }
;       }
;       if (__ballot(alpha[0] != 1.0f || alpha[1] != 1.0f) != 0ull) {
; #pragma unroll
;         for (int qs = 0; qs < 2; ++qs)
; #pragma unroll
;           for (int dt = 0; dt < 8; ++dt) {
;             o[qs][dt][0] *= alpha[qs]; o[qs][dt][1] *= alpha[qs]; o[qs][dt][2] *= alpha[qs]; o[qs][dt][3] *= alpha[qs];
;           }
;       }
; #pragma unroll
;       for (int kk = 0; kk < 2; ++kk)
; #pragma unroll
;         for (int dt = 0; dt < 8; ++dt) {
;           bf16x8 a = *(const bf16x8*)(Vt + (dt * 16 + c) * VT_STRIDE + kk * 32 + quad * 8);
;           o[0][dt] = __builtin_amdgcn_mfma_f32_16x16x32_bf16(a, pb[0][kk], o[0][dt], 0, 0, 0);
;           o[1][dt] = __builtin_amdgcn_mfma_f32_16x16x32_bf16(a, pb[1][kk], o[1][dt], 0, 0, 0);
;         }
	v_mfma_f32_16x16x32_bf16 v[56:59], v[136:139], v[128:131], v[56:59]
	v_exp_f32_e32 v241, v112
	v_fmamk_f32 v112, v113, 0x3e0293ee, v126
	v_exp_f32_e32 v124, v124
	v_mfma_f32_16x16x32_bf16 v[52:55], v[136:139], v[132:135], v[52:55]
	ds_read_b128 v[136:139], v183 offset:31232
	ds_read_b128 v[230:233], v183 offset:28992
	v_exp_f32_e32 v243, v112
	v_fmamk_f32 v112, v114, 0x3e0293ee, v126
	s_waitcnt lgkmcnt(3)
	v_mfma_f32_16x16x32_bf16 v[44:47], v[196:199], v[128:131], v[44:47]
	v_fmac_f32_e32 v126, 0x3e0293ee, v115
	v_exp_f32_e32 v244, v120
	v_exp_f32_e32 v245, v112
	v_mfma_f32_16x16x32_bf16 v[40:43], v[196:199], v[132:135], v[40:43]
	ds_read_b128 v[196:199], v183 offset:33536
	ds_read_b128 v[234:237], v183 offset:31296
	ds_read_b128 v[116:119], v183 offset:33600
	v_exp_f32_e32 v247, v126
	s_waitcnt lgkmcnt(4)
	v_mfma_f32_16x16x32_bf16 v[36:39], v[136:139], v[128:131], v[36:39]
	v_add_f32_e64 v126, v152, v156
	v_add_f32_e64 v127, v153, v157
	v_cvt_pk_bf16_f32 v120, v124, v168
	v_cvt_pk_bf16_f32 v112, v125, v169
	v_mfma_f32_16x16x32_bf16 v[32:35], v[136:139], v[132:135], v[32:35]
	v_add_f32_e64 v124, v124, v168
	v_add_f32_e64 v125, v125, v169
	v_cvt_pk_bf16_f32 v121, v208, v238
	v_cvt_pk_bf16_f32 v122, v240, v242
	s_waitcnt lgkmcnt(2)
	v_mfma_f32_16x16x32_bf16 v[60:63], v[196:199], v[128:131], v[60:63]
	v_add_f32_e64 v128, v154, v158
	v_add_f32_e64 v129, v155, v159
	v_add_f32_e32 v130, v142, v166
	v_add_f32_e32 v131, v143, v167
	v_add_f32_e32 v126, v126, v128
	v_add_f32_e32 v127, v127, v129
	v_mfma_f32_16x16x32_bf16 v[48:51], v[196:199], v[132:135], v[48:51]
	v_add_f32_e64 v128, v140, v164
	v_add_f32_e64 v129, v141, v165
	v_cvt_pk_bf16_f32 v123, v244, v246
	v_add_f32_e32 v128, v128, v130
	v_add_f32_e32 v129, v129, v131
	v_add_f32_e32 v130, v208, v238
	v_add_f32_e32 v131, v209, v239
	v_cvt_pk_bf16_f32 v113, v209, v239
	v_cvt_pk_bf16_f32 v114, v241, v243
	v_cvt_pk_bf16_f32 v115, v245, v247
	v_add_f32_e32 v124, v124, v130
	v_add_f32_e32 v125, v125, v131
	v_add_f32_e32 v130, v240, v242
	v_add_f32_e32 v131, v241, v243
	v_add_f32_e32 v132, v244, v246
	v_add_f32_e32 v133, v245, v247
	v_mfma_f32_16x16x32_bf16 v[92:95], v[200:203], v[120:123], v[92:95]
	v_add_f32_e64 v130, v130, v132
	v_add_f32_e64 v131, v131, v133
	v_add_f32_e32 v126, v126, v128
	v_add_f32_e32 v127, v127, v129
	v_mov_b32_e32 v165, v149
	v_mfma_f32_16x16x32_bf16 v[88:91], v[200:203], v[112:115], v[88:91]
	v_mov_b32_e32 v164, v148
	v_mfma_f32_16x16x32_bf16 v[84:87], v[204:207], v[120:123], v[84:87]
	v_mfma_f32_16x16x32_bf16 v[80:83], v[204:207], v[112:115], v[80:83]
	v_mfma_f32_16x16x32_bf16 v[76:79], v[218:221], v[120:123], v[76:79]
	v_mfma_f32_16x16x32_bf16 v[72:75], v[218:221], v[112:115], v[72:75]
	v_mfma_f32_16x16x32_bf16 v[68:71], v[222:225], v[120:123], v[68:71]
	v_mfma_f32_16x16x32_bf16 v[64:67], v[222:225], v[112:115], v[64:67]
	v_mfma_f32_16x16x32_bf16 v[56:59], v[226:229], v[120:123], v[56:59]
	v_mfma_f32_16x16x32_bf16 v[52:55], v[226:229], v[112:115], v[52:55]
	v_mfma_f32_16x16x32_bf16 v[44:47], v[230:233], v[120:123], v[44:47]
	v_mfma_f32_16x16x32_bf16 v[40:43], v[230:233], v[112:115], v[40:43]
	s_waitcnt lgkmcnt(1)
	v_mfma_f32_16x16x32_bf16 v[36:39], v[234:237], v[120:123], v[36:39]
	v_mfma_f32_16x16x32_bf16 v[32:35], v[234:237], v[112:115], v[32:35]
	s_waitcnt lgkmcnt(0)
	v_mfma_f32_16x16x32_bf16 v[60:63], v[116:119], v[120:123], v[60:63]
	v_add_f32_e64 v120, v124, v130
	v_add_f32_e64 v121, v125, v131
	v_add_f32_e32 v120, v126, v120
	v_add_f32_e32 v121, v127, v121
	v_mfma_f32_16x16x32_bf16 v[48:51], v[116:119], v[112:115], v[48:51]
	v_fma_f32 v194, v194, v150, v120
	v_fma_f32 v195, v195, v151, v121

; template <int MODE> ...
;     ...
;     if (j < jhi) {
;       kp += (size_t)64 * NPAD;
;       vp0 += 64;
;       kr0 = *(const uint4*)kp;
;       kr1 = *(const uint4*)(kp + (size_t)32 * NPAD);
;       vr0 = *(const uint4*)vp0;
;       vr1 = *(const uint4*)(vp0 + (size_t)64 * SEQ);
;     }
;     bool need = true;
;     if (MODE == 0) need = (wunion >> j) & 1ull;
;     if (need) {
;       f32x4 s[2][4];
; #pragma unroll
;       for (int mt = 0; mt < 4; ++mt) {
;         s[0][mt] = (f32x4){0.f, 0.f, 0.f, 0.f};
;         s[1][mt] = (f32x4){0.f, 0.f, 0.f, 0.f};
;       }
; #pragma unroll
;       for (int ks = 0; ks < 4; ++ks)
; #pragma unroll
;         for (int mt = 0; mt < 4; ++mt) {
;           bf16x8 a = *(const bf16x8*)(Kt + (mt * 16 + c) * KT_STRIDE + ks * 32 + quad * 8);
;           s[0][mt] = __builtin_amdgcn_mfma_f32_16x16x32_bf16(a, qf[0][ks], s[0][mt], 0, 0, 0);
;           s[1][mt] = __builtin_amdgcn_mfma_f32_16x16x32_bf16(a, qf[1][ks], s[1][mt], 0, 0, 0);
;         }
;       const bool edge = (j == jhi) || (MODE == 1 && j == jhi - 8);
;       bf16x8 pb[2][2];
;       if (edge) {
; #pragma unroll
;         for (int qs = 0; qs < 2; ++qs) {
;           const int key0 = j * 64 + quad * 4;
;           const int tk = tok[qs];
; #pragma unroll
;           for (int mt = 0; mt < 4; ++mt)
; #pragma unroll
;             for (int jj = 0; jj < 4; ++jj) {
;               const int key = key0 + mt * 16 + jj;
;               bool valid = key <= tk;
;               if (MODE == 1) valid = valid && (key > tk - 512);
;               s[qs][mt][jj] = valid ? s[qs][mt][jj] : RAW_MASKED;
;             }
;         }
;       }
;       float alpha[2];
; #pragma unroll
;       for (int qs = 0; qs < 2; ++qs) {
;         const bool sel = (MODE == 1) ? true : (bool)((mymask[qs] >> j) & 1ull);
;         float mx4[4];
; #pragma unroll
;         for (int mt = 0; mt < 4; ++mt)
;           mx4[mt] = fmaxf(fmaxf(s[qs][mt][0], s[qs][mt][1]), fmaxf(s[qs][mt][2], s[qs][mt][3]));
;         float mx = fmaxf(fmaxf(mx4[0], mx4[1]), fmaxf(mx4[2], mx4[3]));
;         mx = sel ? mx * SCL : -1e30f;
;         mx = quad_max(mx);
;         const float m_new = (mx > m_run[qs] + RESCALE_THR) ? mx : m_run[qs];
;         alpha[qs] = __builtin_amdgcn_exp2f(m_run[qs] - m_new);
.LBB0_323:
	v_add_co_u32_e32 v100, vcc, 0xf4000, v144
	s_lshl_b64 s[8:9], 1, s58
	global_load_dwordx4 v[96:99], v[144:145], off offset:2048
	v_addc_co_u32_e32 v101, vcc, 0, v145, vcc
	v_add_co_u32_e32 v108, vcc, 0x80000, v146
	s_and_b32 s34, s58, 1
	global_load_dwordx4 v[100:103], v[100:101], off offset:2048
	v_addc_co_u32_e32 v109, vcc, 0, v147, vcc
	global_load_dwordx4 v[104:107], v[146:147], off offset:128
	global_load_dwordx4 v[108:111], v[108:109], off offset:128
	s_and_b64 s[10:11], s[8:9], s[16:17]
	s_cmp_eq_u64 s[10:11], 0
	s_cbranch_scc1 .LBB0_322
	s_mul_i32 s10, s34, 0x8c00
	v_add_u32_e32 v167, s10, v178
	v_add_u32_e32 v166, v167, v176
	ds_read_b128 v[112:115], v166
	ds_read_b128 v[116:119], v166 offset:64
	ds_read_b128 v[124:127], v166 offset:4352
	ds_read_b128 v[132:135], v166 offset:4416
	v_and_b32_e32 v169, s9, v163
	v_and_b32_e32 v168, s8, v162
	s_waitcnt lgkmcnt(3)
	v_mfma_f32_16x16x32_bf16 v[120:123], v[112:115], v[8:11], 0
	v_cmp_eq_u64_e64 s[10:11], 0, v[168:169]
	s_waitcnt lgkmcnt(1)
	v_mfma_f32_16x16x32_bf16 v[128:131], v[124:127], v[8:11], 0
	v_mfma_f32_16x16x32_bf16 v[136:139], v[124:127], v[24:27], 0
	ds_read_b128 v[124:127], v166 offset:8704
	ds_read_b128 v[148:151], v166 offset:8768
	ds_read_b128 v[156:159], v166 offset:13056
	ds_read_b128 v[196:199], v166 offset:13120
	ds_read_b128 v[204:207], v166 offset:128
	ds_read_b128 v[218:221], v166 offset:192
	v_mfma_f32_16x16x32_bf16 v[120:123], v[116:119], v[0:3], v[120:123]
	ds_read_b128 v[222:225], v166 offset:4480
	ds_read_b128 v[226:229], v166 offset:4544
	ds_read_b128 v[230:233], v166 offset:8832
	ds_read_b128 v[234:237], v166 offset:8896
	ds_read_b128 v[242:245], v166 offset:13184
	ds_read_b128 v[246:249], v166 offset:13248
	s_waitcnt lgkmcnt(11)
	v_mfma_f32_16x16x32_bf16 v[140:143], v[124:127], v[8:11], 0
	v_mfma_f32_16x16x32_bf16 v[152:155], v[124:127], v[24:27], 0
	s_waitcnt lgkmcnt(9)
	v_mfma_f32_16x16x32_bf16 v[124:127], v[156:159], v[8:11], 0
	v_mfma_f32_16x16x32_bf16 v[128:131], v[132:135], v[0:3], v[128:131]
	s_waitcnt lgkmcnt(7)
	v_mfma_f32_16x16x32_bf16 v[120:123], v[204:207], v[4:7], v[120:123]
	v_mfma_f32_16x16x32_bf16 v[140:143], v[148:151], v[0:3], v[140:143]
	v_mfma_f32_16x16x32_bf16 v[200:203], v[196:199], v[0:3], v[124:127]
	s_waitcnt lgkmcnt(5)
	v_mfma_f32_16x16x32_bf16 v[124:127], v[222:225], v[4:7], v[128:131]
	v_mfma_f32_16x16x32_bf16 v[128:131], v[218:221], v[12:15], v[120:123]
	s_waitcnt lgkmcnt(3)
	v_mfma_f32_16x16x32_bf16 v[238:241], v[230:233], v[4:7], v[140:143]
	v_mfma_f32_16x16x32_bf16 v[140:143], v[226:229], v[12:15], v[124:127]
	s_nop 4
	v_max_f32_e32 v120, v130, v131
	v_max3_f32 v166, v128, v129, v120
	s_waitcnt lgkmcnt(2)
	v_mfma_f32_16x16x32_bf16 v[124:127], v[234:237], v[12:15], v[238:241]
	v_max_f32_e32 v120, v142, v143
	v_max3_f32 v183, v140, v141, v120
	s_waitcnt lgkmcnt(1)
	v_mfma_f32_16x16x32_bf16 v[120:123], v[242:245], v[4:7], v[200:203]
	s_nop 1
	s_waitcnt lgkmcnt(0)
	v_mfma_f32_16x16x32_bf16 v[120:123], v[246:249], v[12:15], v[120:123]
	v_max_f32_e32 v191, v124, v125
	v_mfma_f32_16x16x32_bf16 v[112:115], v[112:115], v[24:27], 0
	v_max_f32_e32 v200, v126, v127
	s_nop 1
	s_nop 2
	v_max_f32_e32 v202, v122, v122
	v_max_f32_e32 v201, v202, v123
	v_max3_f32 v201, v120, v121, v201
	v_mfma_f32_16x16x32_bf16 v[112:115], v[116:119], v[16:19], v[112:115]
	v_max3_f32 v116, v191, v200, v201
	v_max3_f32 v116, v166, v183, v116
	v_mul_f32_e32 v166, 0x3e0293ee, v116
	v_mfma_f32_16x16x32_bf16 v[116:119], v[132:135], v[16:19], v[136:139]
	v_cndmask_b32_e64 v132, v166, v214, s[10:11]
	v_mov_b32_e32 v133, v132
	s_nop 1
	v_permlane16_swap_b32_e32 v132, v133
	v_mfma_f32_16x16x32_bf16 v[112:115], v[204:207], v[20:23], v[112:115]
	v_max_f32_e32 v132, v132, v133
	v_mfma_f32_16x16x32_bf16 v[156:159], v[156:159], v[24:27], 0
	v_mov_b32_e32 v133, v132
	s_nop 1
	v_permlane32_swap_b32_e32 v132, v133
	v_mfma_f32_16x16x32_bf16 v[116:119], v[222:225], v[20:23], v[116:119]
	v_mfma_f32_16x16x32_bf16 v[136:139], v[218:221], v[28:31], v[112:115]
	v_mfma_f32_16x16x32_bf16 v[148:151], v[148:151], v[16:19], v[152:155]
	v_mfma_f32_16x16x32_bf16 v[152:155], v[196:199], v[16:19], v[156:159]
	s_nop 5
	v_max_f32_e32 v112, v138, v139
	v_max_f32_e32 v158, v132, v133
	v_mfma_f32_16x16x32_bf16 v[132:135], v[226:229], v[28:31], v[116:119]
	v_max3_f32 v159, v136, v137, v112
	v_and_b32_e32 v157, s9, v161
	v_and_b32_e32 v156, s8, v160
	v_mfma_f32_16x16x32_bf16 v[112:115], v[230:233], v[20:23], v[148:151]
	v_cmp_eq_u64_e64 s[8:9], 0, v[156:157]
	s_nop 2
	v_max_f32_e32 v116, v134, v135
	v_max3_f32 v148, v132, v133, v116
	v_mfma_f32_16x16x32_bf16 v[116:119], v[234:237], v[28:31], v[112:115]
	s_nop 7
	v_max_f32_e32 v149, v116, v117
	v_mfma_f32_16x16x32_bf16 v[112:115], v[242:245], v[20:23], v[152:155]
	v_max_f32_e32 v150, v118, v119
	v_mfma_f32_16x16x32_bf16 v[112:115], v[246:249], v[28:31], v[112:115]
	s_nop 7
	v_max_f32_e32 v152, v114, v114
	v_max_f32_e32 v151, v152, v115
	v_max3_f32 v151, v112, v113, v151
	v_max3_f32 v149, v149, v150, v151
	v_max3_f32 v148, v159, v148, v149
	v_mul_f32_e32 v148, 0x3e0293ee, v148
	v_cndmask_b32_e64 v148, v148, v214, s[8:9]
	v_mov_b32_e32 v149, v148
	s_nop 1
	v_permlane16_swap_b32_e32 v148, v149
	v_max_f32_e32 v148, v148, v149
	v_mov_b32_e32 v149, v148
	s_nop 1
	v_permlane32_swap_b32_e32 v148, v149
	v_max_f32_e32 v150, v148, v149
	v_add_f32_e32 v148, s46, v164
	v_add_f32_e32 v149, s46, v165
	s_nop 0
	v_cmp_gt_f32_e32 vcc, v150, v149
	s_nop 1
	v_cndmask_b32_e32 v149, v165, v150, vcc
	v_cmp_gt_f32_e32 vcc, v158, v148
	s_nop 1
	v_cndmask_b32_e32 v148, v164, v158, vcc
	v_sub_f32_e32 v150, v164, v148
	v_sub_f32_e32 v151, v165, v149
	s_nop 0
	v_exp_f32_e32 v150, v150
	v_exp_f32_e32 v151, v151
	v_cmp_neq_f32_e32 vcc, 1.0, v150
	v_cmp_neq_f32_e64 s[12:13], 1.0, v151
	s_or_b64 vcc, vcc, s[12:13]
	s_cbranch_vccz .LBB0_321
; template <int MODE> ...
;     ...
;       if (__ballot(alpha[0] != 1.0f || alpha[1] != 1.0f) != 0ull) {
; #pragma unroll
;         for (int qs = 0; qs < 2; ++qs)
; #pragma unroll
;           for (int dt = 0; dt < 8; ++dt) {
;             o[qs][dt][0] *= alpha[qs]; o[qs][dt][1] *= alpha[qs]; o[qs][dt][2] *= alpha[qs]; o[qs][dt][3] *= alpha[qs];
;           }
;       }
	v_mov_b32_e32 v152, v151
	v_pk_mul_f32 v[92:93], v[92:93], v[150:151] op_sel_hi:[1,0]
	v_pk_mul_f32 v[94:95], v[94:95], v[150:151] op_sel_hi:[1,0]
	v_pk_mul_f32 v[84:85], v[84:85], v[150:151] op_sel_hi:[1,0]
	v_pk_mul_f32 v[86:87], v[86:87], v[150:151] op_sel_hi:[1,0]
	v_pk_mul_f32 v[76:77], v[76:77], v[150:151] op_sel_hi:[1,0]
	v_pk_mul_f32 v[78:79], v[78:79], v[150:151] op_sel_hi:[1,0]
	v_pk_mul_f32 v[68:69], v[68:69], v[150:151] op_sel_hi:[1,0]
	v_pk_mul_f32 v[70:71], v[70:71], v[150:151] op_sel_hi:[1,0]
	v_pk_mul_f32 v[56:57], v[56:57], v[150:151] op_sel_hi:[1,0]
	v_pk_mul_f32 v[58:59], v[58:59], v[150:151] op_sel_hi:[1,0]
	v_pk_mul_f32 v[44:45], v[44:45], v[150:151] op_sel_hi:[1,0]
	v_pk_mul_f32 v[46:47], v[46:47], v[150:151] op_sel_hi:[1,0]
	v_pk_mul_f32 v[36:37], v[36:37], v[150:151] op_sel_hi:[1,0]
	v_pk_mul_f32 v[38:39], v[38:39], v[150:151] op_sel_hi:[1,0]
	v_pk_mul_f32 v[60:61], v[60:61], v[150:151] op_sel_hi:[1,0]
	v_pk_mul_f32 v[62:63], v[62:63], v[150:151] op_sel_hi:[1,0]
	v_pk_mul_f32 v[90:91], v[90:91], v[152:153] op_sel_hi:[1,0]
	v_pk_mul_f32 v[88:89], v[88:89], v[152:153] op_sel_hi:[1,0]
	v_pk_mul_f32 v[82:83], v[82:83], v[152:153] op_sel_hi:[1,0]
	v_pk_mul_f32 v[80:81], v[80:81], v[152:153] op_sel_hi:[1,0]
	v_pk_mul_f32 v[74:75], v[74:75], v[152:153] op_sel_hi:[1,0]
	v_pk_mul_f32 v[72:73], v[72:73], v[152:153] op_sel_hi:[1,0]
	v_pk_mul_f32 v[66:67], v[66:67], v[152:153] op_sel_hi:[1,0]
	v_pk_mul_f32 v[64:65], v[64:65], v[152:153] op_sel_hi:[1,0]
	v_pk_mul_f32 v[54:55], v[54:55], v[152:153] op_sel_hi:[1,0]
	v_pk_mul_f32 v[52:53], v[52:53], v[152:153] op_sel_hi:[1,0]
	v_pk_mul_f32 v[42:43], v[42:43], v[152:153] op_sel_hi:[1,0]
	v_pk_mul_f32 v[40:41], v[40:41], v[152:153] op_sel_hi:[1,0]
	v_pk_mul_f32 v[34:35], v[34:35], v[152:153] op_sel_hi:[1,0]
	v_pk_mul_f32 v[32:33], v[32:33], v[152:153] op_sel_hi:[1,0]
	v_pk_mul_f32 v[50:51], v[50:51], v[152:153] op_sel_hi:[1,0]
	v_pk_mul_f32 v[48:49], v[48:49], v[152:153] op_sel_hi:[1,0]
	s_branch .LBB0_321

; template <int MODE> ...
;     ...
;           ps4[mt] = (s[qs][mt][0] + s[qs][mt][1]) + (s[qs][mt][2] + s[qs][mt][3]);
;         }
;         l_run[qs] = l_run[qs] * alpha[qs] + ((ps4[0] + ps4[1]) + (ps4[2] + ps4[3]));
;     ...
;     __syncthreads();
;   }
.LBB0_336:
	v_add_f32_e32 v112, v154, v162
	v_add_f32_e32 v113, v155, v163
	v_add_f32_e32 v114, v142, v160
	v_add_f32_e32 v115, v143, v161
	v_add_f32_e32 v120, v136, v156
	v_add_f32_e32 v121, v137, v157
	v_add_f32_e32 v112, v112, v114
	v_add_f32_e32 v113, v113, v115
	v_add_f32_e32 v114, v140, v158
	v_add_f32_e32 v115, v141, v159
	v_add_f32_e32 v116, v116, v138
	v_add_f32_e32 v117, v117, v139
	v_add_f32_e32 v118, v118, v128
	v_add_f32_e32 v119, v119, v129
	v_add_f32_e32 v114, v114, v120
	v_add_f32_e32 v115, v115, v121
	v_add_f32_e32 v116, v116, v118
	v_add_f32_e32 v117, v117, v119
	v_add_f32_e32 v118, v124, v130
	v_add_f32_e32 v119, v125, v131
	v_add_f32_e32 v120, v126, v132
	v_add_f32_e32 v121, v127, v133
	s_add_i32 s12, s12, 1
	v_add_f32_e32 v118, v118, v120
	v_add_f32_e32 v119, v119, v121
	v_add_f32_e32 v112, v112, v114
	v_add_f32_e32 v113, v113, v115
	v_add_f32_e32 v114, v116, v118
	v_add_f32_e32 v115, v117, v119
	s_add_i32 s8, s13, s12
	v_add_f32_e32 v112, v112, v114
	v_add_f32_e32 v113, v113, v115
	s_add_i32 s16, s16, 64
	s_add_i32 s8, s8, -1
	v_fma_f32 v144, v144, v152, v112
	v_fma_f32 v145, v145, v153, v113
	s_cmp_ge_u32 s8, s96
	s_waitcnt lgkmcnt(0)
	s_barrier
	s_cbranch_scc1 .LBB0_256

; template <int MODE> ...
;     ...
;       float alpha[2];
; #pragma unroll
;       for (int qs = 0; qs < 2; ++qs) {
;         const bool sel = (MODE == 1) ? true : (bool)((mymask[qs] >> j) & 1ull);
;         float mx4[4];
; #pragma unroll
;         for (int mt = 0; mt < 4; ++mt)
;           mx4[mt] = fmaxf(fmaxf(s[qs][mt][0], s[qs][mt][1]), fmaxf(s[qs][mt][2], s[qs][mt][3]));
;         float mx = fmaxf(fmaxf(mx4[0], mx4[1]), fmaxf(mx4[2], mx4[3]));
;         mx = sel ? mx * SCL : -1e30f;
;         mx = quad_max(mx);
;         const float m_new = (mx > m_run[qs] + RESCALE_THR) ? mx : m_run[qs];
;         alpha[qs] = __builtin_amdgcn_exp2f(m_run[qs] - m_new);
;         m_run[qs] = m_new;
;         const float negm = sel ? -m_new : -1e30f;
;         float ps4[4];
; #pragma unroll
;         for (int mt = 0; mt < 4; ++mt) {
; #pragma unroll
;           for (int jj = 0; jj < 4; ++jj) s[qs][mt][jj] = __builtin_amdgcn_exp2f(fmaf(s[qs][mt][jj], SCL, negm));
;           ps4[mt] = (s[qs][mt][0] + s[qs][mt][1]) + (s[qs][mt][2] + s[qs][mt][3]);
;         }
;         l_run[qs] = l_run[qs] * alpha[qs] + ((ps4[0] + ps4[1]) + (ps4[2] + ps4[3]));
; #pragma unroll
;         for (int kk = 0; kk < 2; ++kk) {
;           uint4 pk;
;           pk.x = pack2(s[qs][2 * kk][0], s[qs][2 * kk][1]);
;           pk.y = pack2(s[qs][2 * kk][2], s[qs][2 * kk][3]);
;           pk.z = pack2(s[qs][2 * kk + 1][0], s[qs][2 * kk + 1][1]);
;           pk.w = pack2(s[qs][2 * kk + 1][2], s[qs][2 * kk + 1][3]);
;           pb[qs][kk] = *reinterpret_cast<bf16x8*>(&pk);
;         }
;       }
;       if (__ballot(alpha[0] != 1.0f || alpha[1] != 1.0f) != 0ull) {
; #pragma unroll
;         for (int qs = 0; qs < 2; ++qs)
; #pragma unroll
;           for (int dt = 0; dt < 8; ++dt) {
;             o[qs][dt][0] *= alpha[qs]; o[qs][dt][1] *= alpha[qs]; o[qs][dt][2] *= alpha[qs]; o[qs][dt][3] *= alpha[qs];
;           }
;       }
.LBB0_341:
	v_max_f32_e32 v154, v142, v143
	v_max_f32_e32 v155, v138, v139
	s_nop 0
	v_max_f32_e32 v156, v116, v117
	v_max_f32_e32 v158, v118, v119
	s_nop 0
	v_max_f32_e32 v159, v126, v127
	v_max3_f32 v159, v124, v125, v159
	v_max3_f32 v154, v140, v141, v154
	v_max3_f32 v155, v136, v137, v155
	v_max3_f32 v156, v156, v158, v159
	v_max3_f32 v154, v154, v155, v156
	v_mul_f32_e32 v154, 0x3e0293ee, v154
	v_mov_b32_e32 v155, v154
	s_nop 1
	v_permlane16_swap_b32_e32 v154, v155
	v_max_f32_e32 v154, v154, v155
	v_mov_b32_e32 v155, v154
	s_nop 1
	v_permlane32_swap_b32_e32 v154, v155
	v_max_f32_e32 v156, v154, v155
	v_max_f32_e32 v154, v134, v135
	v_max_f32_e32 v155, v130, v131
	v_max_f32_e32 v158, v112, v113
	v_max_f32_e32 v159, v114, v115
	v_max_f32_e32 v161, v122, v122
	v_max_f32_e32 v160, v161, v123
	v_max3_f32 v160, v120, v121, v160
	v_max3_f32 v154, v132, v133, v154
	v_max3_f32 v155, v128, v129, v155
	v_max3_f32 v158, v158, v159, v160
	v_max3_f32 v154, v154, v155, v158
	v_mul_f32_e32 v154, 0x3e0293ee, v154
	v_mov_b32_e32 v155, v154
	s_nop 1
	v_permlane16_swap_b32_e32 v154, v155
	v_max_f32_e32 v154, v154, v155
	v_mov_b32_e32 v155, v154
	s_nop 1
	v_permlane32_swap_b32_e32 v154, v155
	v_mov_b32_e32 v152, v150
	v_mov_b32_e32 v153, v151
	v_max_f32_e32 v158, v154, v155
	v_add_f32_e32 v154, s46, v152
	v_add_f32_e32 v155, s46, v153
	s_nop 0
	v_cmp_gt_f32_e32 vcc, v158, v155
	s_nop 1
	v_cndmask_b32_e32 v151, v151, v158, vcc
	v_cmp_gt_f32_e32 vcc, v156, v154
	s_nop 1
	v_cndmask_b32_e32 v150, v150, v156, vcc
	v_sub_f32_e32 v152, v152, v150
	v_sub_f32_e32 v153, v153, v151
	s_nop 0
	v_exp_f32_e32 v152, v152
	v_exp_f32_e32 v153, v153
	v_cmp_neq_f32_e32 vcc, 1.0, v152
	v_cmp_neq_f32_e64 s[8:9], 1.0, v153
	s_or_b64 vcc, vcc, s[8:9]
	s_cbranch_vccz .LBB0_343
	v_mov_b32_e32 v154, v153
	v_pk_mul_f32 v[92:93], v[92:93], v[152:153] op_sel_hi:[1,0]
	v_pk_mul_f32 v[94:95], v[94:95], v[152:153] op_sel_hi:[1,0]
	v_pk_mul_f32 v[88:89], v[88:89], v[152:153] op_sel_hi:[1,0]
	v_pk_mul_f32 v[90:91], v[90:91], v[152:153] op_sel_hi:[1,0]
	v_pk_mul_f32 v[84:85], v[84:85], v[152:153] op_sel_hi:[1,0]
	v_pk_mul_f32 v[86:87], v[86:87], v[152:153] op_sel_hi:[1,0]
	v_pk_mul_f32 v[80:81], v[80:81], v[152:153] op_sel_hi:[1,0]
	v_pk_mul_f32 v[82:83], v[82:83], v[152:153] op_sel_hi:[1,0]
	v_pk_mul_f32 v[76:77], v[76:77], v[152:153] op_sel_hi:[1,0]
	v_pk_mul_f32 v[78:79], v[78:79], v[152:153] op_sel_hi:[1,0]
	v_pk_mul_f32 v[72:73], v[72:73], v[152:153] op_sel_hi:[1,0]
	v_pk_mul_f32 v[74:75], v[74:75], v[152:153] op_sel_hi:[1,0]
	v_pk_mul_f32 v[68:69], v[68:69], v[152:153] op_sel_hi:[1,0]
	v_pk_mul_f32 v[70:71], v[70:71], v[152:153] op_sel_hi:[1,0]
	v_pk_mul_f32 v[64:65], v[64:65], v[152:153] op_sel_hi:[1,0]
	v_pk_mul_f32 v[66:67], v[66:67], v[152:153] op_sel_hi:[1,0]
	v_pk_mul_f32 v[62:63], v[62:63], v[154:155] op_sel_hi:[1,0]
	v_pk_mul_f32 v[60:61], v[60:61], v[154:155] op_sel_hi:[1,0]
	v_pk_mul_f32 v[58:59], v[58:59], v[154:155] op_sel_hi:[1,0]
	v_pk_mul_f32 v[56:57], v[56:57], v[154:155] op_sel_hi:[1,0]
	v_pk_mul_f32 v[54:55], v[54:55], v[154:155] op_sel_hi:[1,0]
	v_pk_mul_f32 v[52:53], v[52:53], v[154:155] op_sel_hi:[1,0]
	v_pk_mul_f32 v[50:51], v[50:51], v[154:155] op_sel_hi:[1,0]
	v_pk_mul_f32 v[48:49], v[48:49], v[154:155] op_sel_hi:[1,0]
	v_pk_mul_f32 v[46:47], v[46:47], v[154:155] op_sel_hi:[1,0]
	v_pk_mul_f32 v[44:45], v[44:45], v[154:155] op_sel_hi:[1,0]
	v_pk_mul_f32 v[42:43], v[42:43], v[154:155] op_sel_hi:[1,0]
	v_pk_mul_f32 v[40:41], v[40:41], v[154:155] op_sel_hi:[1,0]
	v_pk_mul_f32 v[38:39], v[38:39], v[154:155] op_sel_hi:[1,0]
	v_pk_mul_f32 v[36:37], v[36:37], v[154:155] op_sel_hi:[1,0]
	v_pk_mul_f32 v[34:35], v[34:35], v[154:155] op_sel_hi:[1,0]
	v_pk_mul_f32 v[32:33], v[32:33], v[154:155] op_sel_hi:[1,0]

; template <int MODE> ...
;     ...
;         const float negm = sel ? -m_new : -1e30f;
;         float ps4[4];
; #pragma unroll
;         for (int mt = 0; mt < 4; ++mt) {
; #pragma unroll
;           for (int jj = 0; jj < 4; ++jj) s[qs][mt][jj] = __builtin_amdgcn_exp2f(fmaf(s[qs][mt][jj], SCL, negm));
;           ps4[mt] = (s[qs][mt][0] + s[qs][mt][1]) + (s[qs][mt][2] + s[qs][mt][3]);
;         }
;         l_run[qs] = l_run[qs] * alpha[qs] + ((ps4[0] + ps4[1]) + (ps4[2] + ps4[3]));
; #pragma unroll
;         for (int kk = 0; kk < 2; ++kk) {
;           uint4 pk;
;           pk.x = pack2(s[qs][2 * kk][0], s[qs][2 * kk][1]);
;           pk.y = pack2(s[qs][2 * kk][2], s[qs][2 * kk][3]);
;           pk.z = pack2(s[qs][2 * kk + 1][0], s[qs][2 * kk + 1][1]);
;           pk.w = pack2(s[qs][2 * kk + 1][2], s[qs][2 * kk + 1][3]);
;           pb[qs][kk] = *reinterpret_cast<bf16x8*>(&pk);
;         }
;       }
;       if (__ballot(alpha[0] != 1.0f || alpha[1] != 1.0f) != 0ull) {
; #pragma unroll
;         for (int qs = 0; qs < 2; ++qs)
; #pragma unroll
;           for (int dt = 0; dt < 8; ++dt) {
;             o[qs][dt][0] *= alpha[qs]; o[qs][dt][1] *= alpha[qs]; o[qs][dt][2] *= alpha[qs]; o[qs][dt][3] *= alpha[qs];
;           }
;       }
; #pragma unroll
;       for (int kk = 0; kk < 2; ++kk)
; #pragma unroll
;         for (int dt = 0; dt < 8; ++dt) {
;           bf16x8 a = *(const bf16x8*)(Vt + (dt * 16 + c) * VT_STRIDE + kk * 32 + quad * 8);
;           o[0][dt] = __builtin_amdgcn_mfma_f32_16x16x32_bf16(a, pb[0][kk], o[0][dt], 0, 0, 0);
;           o[1][dt] = __builtin_amdgcn_mfma_f32_16x16x32_bf16(a, pb[1][kk], o[1][dt], 0, 0, 0);
;         }
.LBB0_657:
	v_cndmask_b32_e64 v165, -v148, v214, s[6:7]
	v_fmamk_f32 v137, v137, 0x3e0293ee, v165
	v_exp_f32_e32 v152, v137
	v_fmamk_f32 v137, v138, 0x3e0293ee, v165
	v_exp_f32_e32 v138, v137
	v_fmamk_f32 v137, v139, 0x3e0293ee, v165
	v_exp_f32_e32 v154, v137
	v_fmamk_f32 v137, v140, 0x3e0293ee, v165
	v_exp_f32_e32 v140, v137
	v_fmamk_f32 v137, v141, 0x3e0293ee, v165
	v_exp_f32_e32 v156, v137
	v_fmamk_f32 v137, v142, 0x3e0293ee, v165
	v_fmamk_f32 v125, v125, 0x3e0293ee, v165
	v_cndmask_b32_e64 v183, -v149, v214, s[10:11]
	v_exp_f32_e32 v142, v137
	v_fmamk_f32 v137, v143, 0x3e0293ee, v165
	v_exp_f32_e32 v164, v125
	v_fmamk_f32 v125, v126, 0x3e0293ee, v165
	v_fmamk_f32 v126, v132, 0x3e0293ee, v183
	v_exp_f32_e32 v158, v137
	v_exp_f32_e32 v137, v126
	v_fmamk_f32 v126, v133, 0x3e0293ee, v183
	v_exp_f32_e32 v153, v126
	v_fmamk_f32 v126, v134, 0x3e0293ee, v183
	v_exp_f32_e32 v139, v126
	v_fmamk_f32 v126, v135, 0x3e0293ee, v183
	v_add_u32_e32 v191, v157, v173
	v_exp_f32_e32 v155, v126
	v_fmamk_f32 v126, v128, 0x3e0293ee, v183
	ds_read_b128 v[132:135], v191 offset:17408
	v_exp_f32_e32 v141, v126
	v_fmamk_f32 v126, v129, 0x3e0293ee, v183
	v_exp_f32_e32 v157, v126
	v_fmamk_f32 v126, v130, 0x3e0293ee, v183
	v_fmamk_f32 v136, v136, 0x3e0293ee, v165
	v_exp_f32_e32 v143, v126
	v_fmamk_f32 v126, v131, 0x3e0293ee, v183
	v_exp_f32_e32 v136, v136
	v_exp_f32_e32 v159, v126
	ds_read_b128 v[196:199], v191 offset:19712
	ds_read_b128 v[200:203], v191 offset:17472
	v_cvt_pk_bf16_f32 v177, v138, v154
	v_cvt_pk_bf16_f32 v176, v136, v152
	v_cvt_pk_bf16_f32 v178, v140, v156
	v_cvt_pk_bf16_f32 v179, v142, v158
	v_cvt_pk_bf16_f32 v128, v137, v153
	v_cvt_pk_bf16_f32 v129, v139, v155
	v_cvt_pk_bf16_f32 v130, v141, v157
	v_cvt_pk_bf16_f32 v131, v143, v159
	s_waitcnt lgkmcnt(2)
	v_mfma_f32_16x16x32_bf16 v[92:95], v[132:135], v[176:179], v[92:95]
	v_fmamk_f32 v120, v120, 0x3e0293ee, v165
	v_exp_f32_e32 v126, v125
	v_fmamk_f32 v125, v127, 0x3e0293ee, v165
	v_mfma_f32_16x16x32_bf16 v[88:91], v[132:135], v[128:131], v[88:91]
	ds_read_b128 v[132:135], v191 offset:22016
	ds_read_b128 v[204:207], v191 offset:19776
	v_exp_f32_e32 v236, v120
	v_fmamk_f32 v120, v121, 0x3e0293ee, v165
	s_waitcnt lgkmcnt(3)
	v_mfma_f32_16x16x32_bf16 v[84:87], v[196:199], v[176:179], v[84:87]
	v_fmamk_f32 v112, v112, 0x3e0293ee, v183
	v_fmamk_f32 v124, v124, 0x3e0293ee, v165
	v_exp_f32_e32 v234, v125
	v_mfma_f32_16x16x32_bf16 v[80:83], v[196:199], v[128:131], v[80:83]
	ds_read_b128 v[196:199], v191 offset:24320
	ds_read_b128 v[208:211], v191 offset:22080
	v_exp_f32_e32 v238, v120
	v_fmamk_f32 v120, v122, 0x3e0293ee, v165
	s_waitcnt lgkmcnt(3)
	v_mfma_f32_16x16x32_bf16 v[76:79], v[132:135], v[176:179], v[76:79]
	v_fmac_f32_e32 v165, 0x3e0293ee, v123
	v_exp_f32_e32 v125, v112
	v_fmamk_f32 v112, v113, 0x3e0293ee, v183
	v_mfma_f32_16x16x32_bf16 v[72:75], v[132:135], v[128:131], v[72:75]
	ds_read_b128 v[132:135], v191 offset:26624
	ds_read_b128 v[218:221], v191 offset:24384
	v_exp_f32_e32 v242, v165
	v_exp_f32_e32 v165, v112
	s_waitcnt lgkmcnt(3)
	v_mfma_f32_16x16x32_bf16 v[68:71], v[196:199], v[176:179], v[68:71]
	v_fmamk_f32 v112, v114, 0x3e0293ee, v183
	v_exp_f32_e32 v127, v112
	v_fmamk_f32 v112, v115, 0x3e0293ee, v183
	v_mfma_f32_16x16x32_bf16 v[64:67], v[196:199], v[128:131], v[64:67]
	ds_read_b128 v[196:199], v191 offset:28928
	ds_read_b128 v[222:225], v191 offset:26688
	v_exp_f32_e32 v235, v112
	v_fmamk_f32 v112, v116, 0x3e0293ee, v183
	s_waitcnt lgkmcnt(3)
; template <int MODE> ...
;     ...
;         for (int mt = 0; mt < 4; ++mt) {
; #pragma unroll
;           for (int jj = 0; jj < 4; ++jj) s[qs][mt][jj] = __builtin_amdgcn_exp2f(fmaf(s[qs][mt][jj], SCL, negm));
;           ps4[mt] = (s[qs][mt][0] + s[qs][mt][1]) + (s[qs][mt][2] + s[qs][mt][3]);
;         }
;         l_run[qs] = l_run[qs] * alpha[qs] + ((ps4[0] + ps4[1]) + (ps4[2] + ps4[3]));
; #pragma unroll
;         for (int kk = 0; kk < 2; ++kk) {
;           uint4 pk;
;           pk.x = pack2(s[qs][2 * kk][0], s[qs][2 * kk][1]);
;           pk.y = pack2(s[qs][2 * kk][2], s[qs][2 * kk][3]);
;           pk.z = pack2(s[qs][2 * kk + 1][0], s[qs][2 * kk + 1][1]);
;           pk.w = pack2(s[qs][2 * kk + 1][2], s[qs][2 * kk + 1][3]);
;           pb[qs][kk] = *reinterpret_cast<bf16x8*>(&pk);
;         }
;       }
;       if (__ballot(alpha[0] != 1.0f || alpha[1] != 1.0f) != 0ull) {
; #pragma unroll
;         for (int qs = 0; qs < 2; ++qs)
; #pragma unroll
;           for (int dt = 0; dt < 8; ++dt) {
;             o[qs][dt][0] *= alpha[qs]; o[qs][dt][1] *= alpha[qs]; o[qs][dt][2] *= alpha[qs]; o[qs][dt][3] *= alpha[qs];
;           }
;       }
; #pragma unroll
;       for (int kk = 0; kk < 2; ++kk)
; #pragma unroll
;         for (int dt = 0; dt < 8; ++dt) {
;           bf16x8 a = *(const bf16x8*)(Vt + (dt * 16 + c) * VT_STRIDE + kk * 32 + quad * 8);
;           o[0][dt] = __builtin_amdgcn_mfma_f32_16x16x32_bf16(a, pb[0][kk], o[0][dt], 0, 0, 0);
;           o[1][dt] = __builtin_amdgcn_mfma_f32_16x16x32_bf16(a, pb[1][kk], o[1][dt], 0, 0, 0);
;         }
	v_mfma_f32_16x16x32_bf16 v[60:63], v[132:135], v[176:179], v[60:63]
	v_exp_f32_e32 v237, v112
	v_fmamk_f32 v116, v117, 0x3e0293ee, v183
	v_exp_f32_e32 v124, v124
	v_mfma_f32_16x16x32_bf16 v[56:59], v[132:135], v[128:131], v[56:59]
	ds_read_b128 v[132:135], v191 offset:31232
	ds_read_b128 v[226:229], v191 offset:28992
	v_exp_f32_e32 v239, v116
	v_fmamk_f32 v116, v118, 0x3e0293ee, v183
	s_waitcnt lgkmcnt(3)
	v_mfma_f32_16x16x32_bf16 v[52:55], v[196:199], v[176:179], v[52:55]
	v_fmac_f32_e32 v183, 0x3e0293ee, v119
	v_exp_f32_e32 v240, v120
	v_exp_f32_e32 v241, v116
	v_mfma_f32_16x16x32_bf16 v[48:51], v[196:199], v[128:131], v[48:51]
	ds_read_b128 v[196:199], v191 offset:33536
	ds_read_b128 v[230:233], v191 offset:31296
	ds_read_b128 v[112:115], v191 offset:33600
	v_exp_f32_e32 v243, v183
	s_waitcnt lgkmcnt(4)
	v_mfma_f32_16x16x32_bf16 v[44:47], v[132:135], v[176:179], v[44:47]
	v_cvt_pk_bf16_f32 v120, v124, v164
	v_cvt_pk_bf16_f32 v121, v126, v234
	v_cvt_pk_bf16_f32 v116, v125, v165
	v_mfma_f32_16x16x32_bf16 v[40:43], v[132:135], v[128:131], v[40:43]
	v_cvt_pk_bf16_f32 v117, v127, v235
	v_add_f32_e32 v132, v142, v158
	v_add_f32_e32 v133, v143, v159
	v_add_f32_e32 v124, v124, v164
	v_add_f32_e32 v125, v125, v165
	s_waitcnt lgkmcnt(2)
	v_mfma_f32_16x16x32_bf16 v[36:39], v[196:199], v[176:179], v[36:39]
	v_add_f32_e64 v126, v126, v234
	v_add_f32_e64 v127, v127, v235
	v_cvt_pk_bf16_f32 v122, v236, v238
	v_cvt_pk_bf16_f32 v123, v240, v242
	v_mfma_f32_16x16x32_bf16 v[32:35], v[196:199], v[128:131], v[32:35]
	v_add_f32_e64 v128, v136, v152
	v_add_f32_e64 v129, v137, v153
	v_add_f32_e32 v130, v138, v154
	v_add_f32_e32 v131, v139, v155
	v_cvt_pk_bf16_f32 v118, v237, v239
	v_add_f32_e32 v128, v128, v130
	v_add_f32_e32 v129, v129, v131
	v_add_f32_e32 v130, v140, v156
	v_add_f32_e32 v131, v141, v157
	v_cvt_pk_bf16_f32 v119, v241, v243
	v_add_f32_e32 v130, v130, v132
	v_add_f32_e32 v131, v131, v133
	v_add_f32_e32 v124, v124, v126
	v_add_f32_e32 v125, v125, v127
	v_add_f32_e32 v126, v236, v238
	v_add_f32_e32 v127, v237, v239
	v_add_f32_e32 v132, v240, v242
	v_add_f32_e32 v133, v241, v243
	v_mfma_f32_16x16x32_bf16 v[92:95], v[200:203], v[120:123], v[92:95]
	v_add_f32_e64 v126, v126, v132
	v_add_f32_e64 v127, v127, v133
	v_add_f32_e32 v128, v128, v130
	v_add_f32_e32 v129, v129, v131
	v_mov_b32_e32 v165, v149
	v_mfma_f32_16x16x32_bf16 v[88:91], v[200:203], v[116:119], v[88:91]
	v_mov_b32_e32 v164, v148
	v_mfma_f32_16x16x32_bf16 v[84:87], v[204:207], v[120:123], v[84:87]
	v_mfma_f32_16x16x32_bf16 v[80:83], v[204:207], v[116:119], v[80:83]
	v_mfma_f32_16x16x32_bf16 v[76:79], v[208:211], v[120:123], v[76:79]
	v_mfma_f32_16x16x32_bf16 v[72:75], v[208:211], v[116:119], v[72:75]
	v_mfma_f32_16x16x32_bf16 v[68:71], v[218:221], v[120:123], v[68:71]
	v_mfma_f32_16x16x32_bf16 v[64:67], v[218:221], v[116:119], v[64:67]
	v_mfma_f32_16x16x32_bf16 v[60:63], v[222:225], v[120:123], v[60:63]
	v_mfma_f32_16x16x32_bf16 v[56:59], v[222:225], v[116:119], v[56:59]
	v_mfma_f32_16x16x32_bf16 v[52:55], v[226:229], v[120:123], v[52:55]
	v_mfma_f32_16x16x32_bf16 v[48:51], v[226:229], v[116:119], v[48:51]
	s_waitcnt lgkmcnt(1)
	v_mfma_f32_16x16x32_bf16 v[44:47], v[230:233], v[120:123], v[44:47]
	v_mfma_f32_16x16x32_bf16 v[40:43], v[230:233], v[116:119], v[40:43]
	s_waitcnt lgkmcnt(0)
	v_mfma_f32_16x16x32_bf16 v[36:39], v[112:115], v[120:123], v[36:39]
	v_add_f32_e64 v120, v124, v126
	v_add_f32_e64 v121, v125, v127
	v_add_f32_e32 v120, v128, v120
	v_add_f32_e32 v121, v129, v121
	v_mfma_f32_16x16x32_bf16 v[32:35], v[112:115], v[116:119], v[32:35]
	v_fma_f32 v194, v194, v150, v120
	v_fma_f32 v195, v195, v151, v121

; template <int MODE> ...
;     ...
;     if (j < jhi) {
;       kp += (size_t)64 * NPAD;
;       vp0 += 64;
;       kr0 = *(const uint4*)kp;
;       kr1 = *(const uint4*)(kp + (size_t)32 * NPAD);
;       vr0 = *(const uint4*)vp0;
;       vr1 = *(const uint4*)(vp0 + (size_t)64 * SEQ);
;     }
;     bool need = true;
;     if (MODE == 0) need = (wunion >> j) & 1ull;
;     if (need) {
;       f32x4 s[2][4];
; #pragma unroll
;       for (int mt = 0; mt < 4; ++mt) {
;         s[0][mt] = (f32x4){0.f, 0.f, 0.f, 0.f};
;         s[1][mt] = (f32x4){0.f, 0.f, 0.f, 0.f};
;       }
; #pragma unroll
;       for (int ks = 0; ks < 4; ++ks)
; #pragma unroll
;         for (int mt = 0; mt < 4; ++mt) {
;           bf16x8 a = *(const bf16x8*)(Kt + (mt * 16 + c) * KT_STRIDE + ks * 32 + quad * 8);
;           s[0][mt] = __builtin_amdgcn_mfma_f32_16x16x32_bf16(a, qf[0][ks], s[0][mt], 0, 0, 0);
;           s[1][mt] = __builtin_amdgcn_mfma_f32_16x16x32_bf16(a, qf[1][ks], s[1][mt], 0, 0, 0);
;         }
;       const bool edge = (j == jhi) || (MODE == 1 && j == jhi - 8);
;       bf16x8 pb[2][2];
;       if (edge) {
; #pragma unroll
;         for (int qs = 0; qs < 2; ++qs) {
;           const int key0 = j * 64 + quad * 4;
;           const int tk = tok[qs];
; #pragma unroll
;           for (int mt = 0; mt < 4; ++mt)
; #pragma unroll
;             for (int jj = 0; jj < 4; ++jj) {
;               const int key = key0 + mt * 16 + jj;
;               bool valid = key <= tk;
;               if (MODE == 1) valid = valid && (key > tk - 512);
;               s[qs][mt][jj] = valid ? s[qs][mt][jj] : RAW_MASKED;
;             }
;         }
;       }
;       float alpha[2];
; #pragma unroll
;       for (int qs = 0; qs < 2; ++qs) {
;         const bool sel = (MODE == 1) ? true : (bool)((mymask[qs] >> j) & 1ull);
;         float mx4[4];
; #pragma unroll
;         for (int mt = 0; mt < 4; ++mt)
;           mx4[mt] = fmaxf(fmaxf(s[qs][mt][0], s[qs][mt][1]), fmaxf(s[qs][mt][2], s[qs][mt][3]));
;         float mx = fmaxf(fmaxf(mx4[0], mx4[1]), fmaxf(mx4[2], mx4[3]));
;         mx = sel ? mx * SCL : -1e30f;
;         mx = quad_max(mx);
;         const float m_new = (mx > m_run[qs] + RESCALE_THR) ? mx : m_run[qs];
;         alpha[qs] = __builtin_amdgcn_exp2f(m_run[qs] - m_new);
;         m_run[qs] = m_new;
;         const float negm = sel ? -m_new : -1e30f;
.LBB0_659:
	v_add_co_u32_e32 v100, vcc, 0xf4000, v144
	s_lshl_b64 s[10:11], 1, s60
	global_load_dwordx4 v[96:99], v[144:145], off offset:2048
	v_addc_co_u32_e32 v101, vcc, 0, v145, vcc
	v_add_co_u32_e32 v108, vcc, 0x80000, v146
	s_and_b32 s8, s60, 1
	global_load_dwordx4 v[100:103], v[100:101], off offset:2048
	v_addc_co_u32_e32 v109, vcc, 0, v147, vcc
	global_load_dwordx4 v[104:107], v[146:147], off offset:128
	global_load_dwordx4 v[108:111], v[108:109], off offset:128
	s_and_b64 s[6:7], s[10:11], s[16:17]
	s_cmp_eq_u64 s[6:7], 0
	s_cbranch_scc1 .LBB0_658
	s_mul_i32 s6, s8, 0x8c00
	v_add_u32_e32 v157, s6, v174
	v_add_u32_e32 v156, v157, v171
	ds_read_b128 v[112:115], v156
	ds_read_b128 v[148:151], v156 offset:64
	ds_read_b128 v[120:123], v156 offset:4352
	ds_read_b128 v[128:131], v156 offset:8704
	ds_read_b128 v[136:139], v156 offset:13056
	s_waitcnt lgkmcnt(4)
	v_mfma_f32_16x16x32_bf16 v[116:119], v[112:115], v[8:11], 0
	v_mfma_f32_16x16x32_bf16 v[112:115], v[112:115], v[24:27], 0
	s_waitcnt lgkmcnt(3)
	v_mfma_f32_16x16x32_bf16 v[116:119], v[148:151], v[0:3], v[116:119]
	v_mfma_f32_16x16x32_bf16 v[112:115], v[148:151], v[16:19], v[112:115]
	ds_read_b128 v[148:151], v156 offset:4416
	s_waitcnt lgkmcnt(3)
	v_mfma_f32_16x16x32_bf16 v[124:127], v[120:123], v[8:11], 0
	v_mfma_f32_16x16x32_bf16 v[120:123], v[120:123], v[24:27], 0
	s_waitcnt lgkmcnt(0)
	v_mfma_f32_16x16x32_bf16 v[124:127], v[148:151], v[0:3], v[124:127]
	v_mfma_f32_16x16x32_bf16 v[120:123], v[148:151], v[16:19], v[120:123]
	ds_read_b128 v[148:151], v156 offset:8768
	v_mfma_f32_16x16x32_bf16 v[132:135], v[128:131], v[8:11], 0
	v_mfma_f32_16x16x32_bf16 v[128:131], v[128:131], v[24:27], 0
	s_waitcnt lgkmcnt(0)
	v_mfma_f32_16x16x32_bf16 v[132:135], v[148:151], v[0:3], v[132:135]
	v_mfma_f32_16x16x32_bf16 v[128:131], v[148:151], v[16:19], v[128:131]
	ds_read_b128 v[148:151], v156 offset:13120
	v_mfma_f32_16x16x32_bf16 v[140:143], v[136:139], v[8:11], 0
	v_mfma_f32_16x16x32_bf16 v[136:139], v[136:139], v[24:27], 0
	s_waitcnt lgkmcnt(0)
	v_mfma_f32_16x16x32_bf16 v[140:143], v[148:151], v[0:3], v[140:143]
	v_mfma_f32_16x16x32_bf16 v[136:139], v[148:151], v[16:19], v[136:139]
	ds_read_b128 v[148:151], v156 offset:128
	s_waitcnt lgkmcnt(0)
	v_mfma_f32_16x16x32_bf16 v[116:119], v[148:151], v[4:7], v[116:119]
	v_mfma_f32_16x16x32_bf16 v[112:115], v[148:151], v[20:23], v[112:115]
	ds_read_b128 v[148:151], v156 offset:4480
	s_waitcnt lgkmcnt(0)
	v_mfma_f32_16x16x32_bf16 v[124:127], v[148:151], v[4:7], v[124:127]
	v_mfma_f32_16x16x32_bf16 v[120:123], v[148:151], v[20:23], v[120:123]
	ds_read_b128 v[148:151], v156 offset:8832
	s_waitcnt lgkmcnt(0)
	v_mfma_f32_16x16x32_bf16 v[152:155], v[148:151], v[4:7], v[132:135]
	v_mfma_f32_16x16x32_bf16 v[148:151], v[148:151], v[20:23], v[128:131]
	s_nop 2
	ds_read_b128 v[128:131], v156 offset:13184
	s_waitcnt lgkmcnt(0)
	v_mfma_f32_16x16x32_bf16 v[176:179], v[128:131], v[4:7], v[140:143]
	v_mfma_f32_16x16x32_bf16 v[196:199], v[128:131], v[20:23], v[136:139]
	ds_read_b128 v[128:131], v156 offset:192
	s_waitcnt lgkmcnt(0)
	v_mfma_f32_16x16x32_bf16 v[132:135], v[128:131], v[28:31], v[112:115]
	s_nop 2
	ds_read_b128 v[112:115], v156 offset:4544
	v_mfma_f32_16x16x32_bf16 v[136:139], v[128:131], v[12:15], v[116:119]
	s_nop 2
	ds_read_b128 v[116:119], v156 offset:13248
	s_waitcnt lgkmcnt(1)
	v_mfma_f32_16x16x32_bf16 v[140:143], v[112:115], v[12:15], v[124:127]
	v_mfma_f32_16x16x32_bf16 v[128:131], v[112:115], v[28:31], v[120:123]
	ds_read_b128 v[112:115], v156 offset:8896
	s_waitcnt lgkmcnt(0)
	v_mfma_f32_16x16x32_bf16 v[124:127], v[112:115], v[12:15], v[152:155]
	s_nop 3
	s_nop 2
	v_mfma_f32_16x16x32_bf16 v[112:115], v[112:115], v[28:31], v[148:151]
	v_mfma_f32_16x16x32_bf16 v[120:123], v[116:119], v[12:15], v[176:179]
	s_nop 0
	s_nop 0
	v_max_f32_e32 v150, v138, v139
	v_max_f32_e32 v151, v142, v143
	v_max_f32_e32 v152, v124, v125
	v_max_f32_e32 v153, v126, v127
	s_nop 1
	v_max_f32_e32 v154, v122, v123
	v_and_b32_e32 v149, s11, v163
	v_and_b32_e32 v148, s10, v162
	v_max3_f32 v154, v120, v121, v154
	v_max3_f32 v150, v136, v137, v150
	v_max3_f32 v151, v140, v141, v151
	v_cmp_eq_u64_e64 s[6:7], 0, v[148:149]
	v_max3_f32 v148, v152, v153, v154
	v_max3_f32 v148, v150, v151, v148
	v_mul_f32_e32 v148, 0x3e0293ee, v148
	v_cndmask_b32_e64 v148, v148, v214, s[6:7]
	v_mov_b32_e32 v149, v148
	v_mfma_f32_16x16x32_bf16 v[116:119], v[116:119], v[28:31], v[196:199]
	s_nop 0
	v_permlane16_swap_b32_e32 v148, v149
	v_max_f32_e32 v151, v134, v135
	v_max_f32_e32 v148, v148, v149
	v_max_f32_e32 v152, v130, v131
	v_mov_b32_e32 v149, v148
	v_max_f32_e32 v153, v112, v113
	s_nop 0
	v_permlane32_swap_b32_e32 v148, v149
	v_max_f32_e32 v154, v114, v115
	v_max_f32_e32 v156, v118, v118
	v_max_f32_e32 v155, v156, v119
	v_max_f32_e32 v150, v148, v149
	v_and_b32_e32 v149, s11, v161
	v_and_b32_e32 v148, s10, v160
	v_max3_f32 v155, v116, v117, v155
	v_max3_f32 v151, v132, v133, v151
	v_max3_f32 v152, v128, v129, v152
	v_cmp_eq_u64_e64 s[10:11], 0, v[148:149]
	v_max3_f32 v148, v153, v154, v155
	v_max3_f32 v148, v151, v152, v148
	v_mul_f32_e32 v148, 0x3e0293ee, v148
	v_cndmask_b32_e64 v148, v148, v214, s[10:11]
	v_mov_b32_e32 v149, v148
	s_nop 1
	v_permlane16_swap_b32_e32 v148, v149
	v_max_f32_e32 v148, v148, v149
	v_mov_b32_e32 v149, v148
	s_nop 1
	v_permlane32_swap_b32_e32 v148, v149
	v_max_f32_e32 v151, v148, v149
	v_add_f32_e32 v148, s48, v164
	v_add_f32_e32 v149, s48, v165
	s_nop 0
	v_cmp_gt_f32_e32 vcc, v150, v148
	v_cmp_gt_f32_e64 s[12:13], v151, v149
	s_nop 0
	v_cndmask_b32_e32 v148, v164, v150, vcc
	v_cndmask_b32_e64 v149, v165, v151, s[12:13]
	v_sub_f32_e32 v150, v164, v148
	v_sub_f32_e32 v151, v165, v149
	s_nop 0
	v_exp_f32_e32 v150, v150
	v_exp_f32_e32 v151, v151
	v_cmp_neq_f32_e32 vcc, 1.0, v150
	v_cmp_neq_f32_e64 s[12:13], 1.0, v151
	s_or_b64 vcc, vcc, s[12:13]
	s_cbranch_vccz .LBB0_657
; template <int MODE> ...
;     ...
;       if (__ballot(alpha[0] != 1.0f || alpha[1] != 1.0f) != 0ull) {
; #pragma unroll
;         for (int qs = 0; qs < 2; ++qs)
; #pragma unroll
;           for (int dt = 0; dt < 8; ++dt) {
;             o[qs][dt][0] *= alpha[qs]; o[qs][dt][1] *= alpha[qs]; o[qs][dt][2] *= alpha[qs]; o[qs][dt][3] *= alpha[qs];
;           }
;       }
	v_mov_b32_e32 v152, v151
	v_pk_mul_f32 v[92:93], v[92:93], v[150:151] op_sel_hi:[1,0]
	v_pk_mul_f32 v[94:95], v[94:95], v[150:151] op_sel_hi:[1,0]
	v_pk_mul_f32 v[84:85], v[84:85], v[150:151] op_sel_hi:[1,0]
	v_pk_mul_f32 v[86:87], v[86:87], v[150:151] op_sel_hi:[1,0]
	v_pk_mul_f32 v[76:77], v[76:77], v[150:151] op_sel_hi:[1,0]
	v_pk_mul_f32 v[78:79], v[78:79], v[150:151] op_sel_hi:[1,0]
	v_pk_mul_f32 v[68:69], v[68:69], v[150:151] op_sel_hi:[1,0]
	v_pk_mul_f32 v[70:71], v[70:71], v[150:151] op_sel_hi:[1,0]
	v_pk_mul_f32 v[60:61], v[60:61], v[150:151] op_sel_hi:[1,0]
	v_pk_mul_f32 v[62:63], v[62:63], v[150:151] op_sel_hi:[1,0]
	v_pk_mul_f32 v[52:53], v[52:53], v[150:151] op_sel_hi:[1,0]
	v_pk_mul_f32 v[54:55], v[54:55], v[150:151] op_sel_hi:[1,0]
	v_pk_mul_f32 v[44:45], v[44:45], v[150:151] op_sel_hi:[1,0]
	v_pk_mul_f32 v[46:47], v[46:47], v[150:151] op_sel_hi:[1,0]
	v_pk_mul_f32 v[36:37], v[36:37], v[150:151] op_sel_hi:[1,0]
	v_pk_mul_f32 v[38:39], v[38:39], v[150:151] op_sel_hi:[1,0]
	v_pk_mul_f32 v[90:91], v[90:91], v[152:153] op_sel_hi:[1,0]
	v_pk_mul_f32 v[88:89], v[88:89], v[152:153] op_sel_hi:[1,0]
	v_pk_mul_f32 v[82:83], v[82:83], v[152:153] op_sel_hi:[1,0]
	v_pk_mul_f32 v[80:81], v[80:81], v[152:153] op_sel_hi:[1,0]
	v_pk_mul_f32 v[74:75], v[74:75], v[152:153] op_sel_hi:[1,0]
	v_pk_mul_f32 v[72:73], v[72:73], v[152:153] op_sel_hi:[1,0]
	v_pk_mul_f32 v[66:67], v[66:67], v[152:153] op_sel_hi:[1,0]
	v_pk_mul_f32 v[64:65], v[64:65], v[152:153] op_sel_hi:[1,0]
	v_pk_mul_f32 v[58:59], v[58:59], v[152:153] op_sel_hi:[1,0]
	v_pk_mul_f32 v[56:57], v[56:57], v[152:153] op_sel_hi:[1,0]
	v_pk_mul_f32 v[50:51], v[50:51], v[152:153] op_sel_hi:[1,0]
	v_pk_mul_f32 v[48:49], v[48:49], v[152:153] op_sel_hi:[1,0]
	v_pk_mul_f32 v[42:43], v[42:43], v[152:153] op_sel_hi:[1,0]
	v_pk_mul_f32 v[40:41], v[40:41], v[152:153] op_sel_hi:[1,0]
	v_pk_mul_f32 v[34:35], v[34:35], v[152:153] op_sel_hi:[1,0]
	v_pk_mul_f32 v[32:33], v[32:33], v[152:153] op_sel_hi:[1,0]
	s_branch .LBB0_657

; template <int MODE> ...
;     ...
;           ps4[mt] = (s[qs][mt][0] + s[qs][mt][1]) + (s[qs][mt][2] + s[qs][mt][3]);
;         }
;         l_run[qs] = l_run[qs] * alpha[qs] + ((ps4[0] + ps4[1]) + (ps4[2] + ps4[3]));
;     ...
;     if (j < jhi) {
;       stage_write_k((bf16_t*)(smem + (cb ^ 1) * STAGE_BYTES), krow0, kch, kr0, kr1);
;       stage_write_v((bf16_t*)(smem + (cb ^ 1) * STAGE_BYTES + KT_BYTES), vrow0, vch, vr0, vr1);
;     }
;     __syncthreads();
;   }
.LBB0_672:
	v_add_f32_e32 v112, v154, v162
	v_add_f32_e32 v113, v155, v163
	v_add_f32_e32 v114, v142, v160
	v_add_f32_e32 v115, v143, v161
	v_add_f32_e32 v116, v136, v156
	v_add_f32_e32 v117, v137, v157
	v_add_f32_e32 v112, v112, v114
	v_add_f32_e32 v113, v113, v115
	v_add_f32_e32 v114, v140, v158
	v_add_f32_e32 v115, v141, v159
	v_add_f32_e32 v118, v126, v128
	v_add_f32_e32 v119, v127, v129
	v_add_f32_e32 v114, v114, v116
	v_add_f32_e32 v115, v115, v117
	v_add_f32_e32 v116, v124, v138
	v_add_f32_e32 v117, v125, v139
	s_add_i32 s8, s8, 1
	v_add_f32_e32 v116, v116, v118
	v_add_f32_e32 v117, v117, v119
	v_add_f32_e32 v118, v120, v130
	v_add_f32_e32 v119, v121, v131
	v_add_f32_e32 v120, v122, v132
	v_add_f32_e32 v121, v123, v133
	v_add_f32_e32 v112, v112, v114
	v_add_f32_e32 v113, v113, v115
	v_add_f32_e32 v118, v118, v120
	v_add_f32_e32 v119, v119, v121
	s_add_i32 s6, s9, s8
	v_add_f32_e32 v114, v116, v118
	v_add_f32_e32 v115, v117, v119
	s_add_i32 s14, s14, 64
	v_add_f32_e32 v112, v112, v114
	v_add_f32_e32 v113, v113, v115
	s_add_i32 s6, s6, -1
	v_fma_f32 v144, v144, v152, v112
	v_fma_f32 v145, v145, v153, v113
	s_cmp_ge_u32 s6, s96
	s_waitcnt lgkmcnt(0)
	s_barrier
	s_cbranch_scc1 .LBB0_592

; template <int MODE> ...
;     ...
;       for (int qs = 0; qs < 2; ++qs) {
;         const bool sel = (MODE == 1) ? true : (bool)((mymask[qs] >> j) & 1ull);
;         float mx4[4];
; #pragma unroll
;         for (int mt = 0; mt < 4; ++mt)
;           mx4[mt] = fmaxf(fmaxf(s[qs][mt][0], s[qs][mt][1]), fmaxf(s[qs][mt][2], s[qs][mt][3]));
;         float mx = fmaxf(fmaxf(mx4[0], mx4[1]), fmaxf(mx4[2], mx4[3]));
;         mx = sel ? mx * SCL : -1e30f;
;         mx = quad_max(mx);
;         const float m_new = (mx > m_run[qs] + RESCALE_THR) ? mx : m_run[qs];
;         alpha[qs] = __builtin_amdgcn_exp2f(m_run[qs] - m_new);
;         m_run[qs] = m_new;
;         const float negm = sel ? -m_new : -1e30f;
;         float ps4[4];
; #pragma unroll
;         for (int mt = 0; mt < 4; ++mt) {
; #pragma unroll
;           for (int jj = 0; jj < 4; ++jj) s[qs][mt][jj] = __builtin_amdgcn_exp2f(fmaf(s[qs][mt][jj], SCL, negm));
;           ps4[mt] = (s[qs][mt][0] + s[qs][mt][1]) + (s[qs][mt][2] + s[qs][mt][3]);
;         }
;         l_run[qs] = l_run[qs] * alpha[qs] + ((ps4[0] + ps4[1]) + (ps4[2] + ps4[3]));
; #pragma unroll
;         for (int kk = 0; kk < 2; ++kk) {
;           uint4 pk;
;           pk.x = pack2(s[qs][2 * kk][0], s[qs][2 * kk][1]);
;           pk.y = pack2(s[qs][2 * kk][2], s[qs][2 * kk][3]);
;           pk.z = pack2(s[qs][2 * kk + 1][0], s[qs][2 * kk + 1][1]);
;           pk.w = pack2(s[qs][2 * kk + 1][2], s[qs][2 * kk + 1][3]);
;           pb[qs][kk] = *reinterpret_cast<bf16x8*>(&pk);
;         }
;       }
;       if (__ballot(alpha[0] != 1.0f || alpha[1] != 1.0f) != 0ull) {
; #pragma unroll
;         for (int qs = 0; qs < 2; ++qs)
; #pragma unroll
;           for (int dt = 0; dt < 8; ++dt) {
;             o[qs][dt][0] *= alpha[qs]; o[qs][dt][1] *= alpha[qs]; o[qs][dt][2] *= alpha[qs]; o[qs][dt][3] *= alpha[qs];
;           }
;       }
.LBB0_677:
	v_max_f32_e32 v154, v142, v143
	v_max_f32_e32 v155, v138, v139
	s_nop 0
	v_max_f32_e32 v156, v124, v125
	v_max_f32_e32 v158, v126, v127
	s_nop 0
	v_max_f32_e32 v159, v122, v123
	v_max3_f32 v159, v120, v121, v159
	v_max3_f32 v154, v140, v141, v154
	v_max3_f32 v155, v136, v137, v155
	v_max3_f32 v156, v156, v158, v159
	v_max3_f32 v154, v154, v155, v156
	v_mul_f32_e32 v154, 0x3e0293ee, v154
	v_mov_b32_e32 v155, v154
	s_nop 1
	v_permlane16_swap_b32_e32 v154, v155
	v_max_f32_e32 v154, v154, v155
	v_mov_b32_e32 v155, v154
	s_nop 1
	v_permlane32_swap_b32_e32 v154, v155
	v_max_f32_e32 v156, v154, v155
	v_max_f32_e32 v154, v134, v135
	v_max_f32_e32 v155, v130, v131
	v_max_f32_e32 v158, v112, v113
	v_max_f32_e32 v159, v114, v115
	v_max_f32_e32 v161, v118, v118
	v_max_f32_e32 v160, v161, v119
	v_max3_f32 v160, v116, v117, v160
	v_max3_f32 v154, v132, v133, v154
	v_max3_f32 v155, v128, v129, v155
	v_max3_f32 v158, v158, v159, v160
	v_max3_f32 v154, v154, v155, v158
	v_mul_f32_e32 v154, 0x3e0293ee, v154
	v_mov_b32_e32 v155, v154
	s_nop 1
	v_permlane16_swap_b32_e32 v154, v155
	v_max_f32_e32 v154, v154, v155
	v_mov_b32_e32 v155, v154
	s_nop 1
	v_permlane32_swap_b32_e32 v154, v155
	v_mov_b32_e32 v152, v150
	v_mov_b32_e32 v153, v151
	v_max_f32_e32 v158, v154, v155
	v_add_f32_e32 v154, s48, v152
	v_add_f32_e32 v155, s48, v153
	s_nop 0
	v_cmp_gt_f32_e32 vcc, v158, v155
	s_nop 1
	v_cndmask_b32_e32 v151, v151, v158, vcc
	v_cmp_gt_f32_e32 vcc, v156, v154
	s_nop 1
	v_cndmask_b32_e32 v150, v150, v156, vcc
	v_sub_f32_e32 v152, v152, v150
	v_sub_f32_e32 v153, v153, v151
	s_nop 0
	v_exp_f32_e32 v152, v152
	v_exp_f32_e32 v153, v153
	v_cmp_neq_f32_e32 vcc, 1.0, v152
	v_cmp_neq_f32_e64 s[6:7], 1.0, v153
	s_or_b64 vcc, vcc, s[6:7]
	s_cbranch_vccz .LBB0_679
	v_mov_b32_e32 v154, v153
	v_pk_mul_f32 v[92:93], v[92:93], v[152:153] op_sel_hi:[1,0]
	v_pk_mul_f32 v[94:95], v[94:95], v[152:153] op_sel_hi:[1,0]
	v_pk_mul_f32 v[88:89], v[88:89], v[152:153] op_sel_hi:[1,0]
	v_pk_mul_f32 v[90:91], v[90:91], v[152:153] op_sel_hi:[1,0]
	v_pk_mul_f32 v[84:85], v[84:85], v[152:153] op_sel_hi:[1,0]
	v_pk_mul_f32 v[86:87], v[86:87], v[152:153] op_sel_hi:[1,0]
	v_pk_mul_f32 v[80:81], v[80:81], v[152:153] op_sel_hi:[1,0]
	v_pk_mul_f32 v[82:83], v[82:83], v[152:153] op_sel_hi:[1,0]
	v_pk_mul_f32 v[76:77], v[76:77], v[152:153] op_sel_hi:[1,0]
	v_pk_mul_f32 v[78:79], v[78:79], v[152:153] op_sel_hi:[1,0]
	v_pk_mul_f32 v[72:73], v[72:73], v[152:153] op_sel_hi:[1,0]
	v_pk_mul_f32 v[74:75], v[74:75], v[152:153] op_sel_hi:[1,0]
	v_pk_mul_f32 v[68:69], v[68:69], v[152:153] op_sel_hi:[1,0]
	v_pk_mul_f32 v[70:71], v[70:71], v[152:153] op_sel_hi:[1,0]
	v_pk_mul_f32 v[64:65], v[64:65], v[152:153] op_sel_hi:[1,0]
	v_pk_mul_f32 v[66:67], v[66:67], v[152:153] op_sel_hi:[1,0]
	v_pk_mul_f32 v[62:63], v[62:63], v[154:155] op_sel_hi:[1,0]
	v_pk_mul_f32 v[60:61], v[60:61], v[154:155] op_sel_hi:[1,0]
	v_pk_mul_f32 v[58:59], v[58:59], v[154:155] op_sel_hi:[1,0]
	v_pk_mul_f32 v[56:57], v[56:57], v[154:155] op_sel_hi:[1,0]
	v_pk_mul_f32 v[54:55], v[54:55], v[154:155] op_sel_hi:[1,0]
	v_pk_mul_f32 v[52:53], v[52:53], v[154:155] op_sel_hi:[1,0]
	v_pk_mul_f32 v[50:51], v[50:51], v[154:155] op_sel_hi:[1,0]
	v_pk_mul_f32 v[48:49], v[48:49], v[154:155] op_sel_hi:[1,0]
	v_pk_mul_f32 v[46:47], v[46:47], v[154:155] op_sel_hi:[1,0]
	v_pk_mul_f32 v[44:45], v[44:45], v[154:155] op_sel_hi:[1,0]
	v_pk_mul_f32 v[42:43], v[42:43], v[154:155] op_sel_hi:[1,0]
	v_pk_mul_f32 v[40:41], v[40:41], v[154:155] op_sel_hi:[1,0]
	v_pk_mul_f32 v[38:39], v[38:39], v[154:155] op_sel_hi:[1,0]
	v_pk_mul_f32 v[36:37], v[36:37], v[154:155] op_sel_hi:[1,0]
	v_pk_mul_f32 v[34:35], v[34:35], v[154:155] op_sel_hi:[1,0]
	v_pk_mul_f32 v[32:33], v[32:33], v[154:155] op_sel_hi:[1,0]
